# plus FoX attention: next-chunk K/V prefetch loads issued together (dropped the per-load vmcnt(0) that serialized six round trips per chunk)
# speedup vs baseline: 1.0197x; 1.0002x over previous
.LBB0_308:
	s_or_b64 exec, exec, s[6:7]
	v_cmp_gt_i32_e64 s[40:41], s60, v209
	s_and_saveexec_b64 s[6:7], s[40:41]
	s_cbranch_execz .LBB0_310
	v_lshl_add_u32 v0, v209, 6, 64
	v_mad_i64_i32 v[4:5], s[10:11], v0, s18, v[150:151]
	s_nop 0
	flat_load_dwordx4 v[108:111], v[4:5] offset:2560
.LBB0_310:
	s_or_b64 exec, exec, s[6:7]
	v_add_u32_e32 v0, 2, v209
	v_cmp_ge_i32_e64 s[40:41], s60, v0
	s_and_saveexec_b64 s[6:7], s[40:41]
	s_cbranch_execz .LBB0_312
	v_lshlrev_b32_e32 v0, 6, v0
	v_mad_i64_i32 v[4:5], s[10:11], v0, s18, v[150:151]
	s_nop 0
	flat_load_dwordx4 v[112:115], v[4:5] offset:2560

.LBB0_315:
	v_lshl_add_u64 v[2:3], v[2:3], 0, v[166:167]
	v_lshl_add_u64 v[2:3], v[156:157], 1, v[2:3]
	s_nop 0
	flat_load_dwordx4 v[124:127], v[2:3]

.LBB0_340:
	v_lshl_add_u64 v[4:5], v[2:3], 0, v[162:163]
	v_lshl_add_u64 v[4:5], v[152:153], 1, v[4:5]
	s_nop 0
	flat_load_dwordx4 v[116:119], v[4:5]
	s_or_b64 exec, exec, s[6:7]
	v_cmp_le_i32_e64 s[40:41], v209, v200
	s_and_saveexec_b64 s[6:7], s[40:41]
	s_cbranch_execz .LBB0_314
.LBB0_341:
	v_lshl_add_u64 v[4:5], v[2:3], 0, v[164:165]
	v_lshl_add_u64 v[4:5], v[154:155], 1, v[4:5]
	s_nop 0
	flat_load_dwordx4 v[120:123], v[4:5]
	s_or_b64 exec, exec, s[6:7]
	v_cmp_le_i32_e64 s[40:41], v209, v201
	s_and_saveexec_b64 s[6:7], s[40:41]
	s_cbranch_execnz .LBB0_315
	s_branch .LBB0_316
